# GEMM super-phase closing barrier taken 4 MFMAs before the end of the 32-MFMA block (tail MFMAs cover the barrier release)
# baseline (speedup 1.0000x reference)
; #define PG8_STAGE(bufoff, gbase, voff) do { _Pragma("unroll") for (int _i = 0; _i < 2; ++_i) \
;         __builtin_amdgcn_global_load_lds((const unsigned*)((const char*)(gbase) + (voff)[_i]), (PG8_LAS unsigned*)(lds + (bufoff) + ldsw + _i * 8192), 16, 0, 0); } while (0)
; #define PG8_LDA(dst, b, h) do { _Pragma("unroll") for (int m = 0; m < 4; ++m) _Pragma("unroll") for (int k = 0; k < 2; ++k) dst[m][k] = *(const PG8_LAS bf16x8*)(lds + PG8_SA(b, h) + aoff + m * 2048 + k * 1024); } while (0)
; #define PG8_LDB(dst, b, h) do { _Pragma("unroll") for (int n = 0; n < 2; ++n) _Pragma("unroll") for (int k = 0; k < 2; ++k) dst[n][k] = *(const PG8_LAS bf16x8*)(lds + PG8_SB(b, h) + boff + n * 2048 + k * 1024); } while (0)
; #define PG8_MMA(ai, bj, At, Bt) do { __builtin_amdgcn_s_setprio(1); _Pragma("unroll") for (int m = 0; m < 4; ++m) _Pragma("unroll") for (int n = 0; n < 2; ++n) _Pragma("unroll") for (int k = 0; k < 2; ++k) \
;         acc[ai][bj][m][n] = __builtin_amdgcn_mfma_f32_16x16x32_bf16(Bt[n][k], At[m][k], acc[ai][bj][m][n], 0, 0, 0); __builtin_amdgcn_s_setprio(0); } while (0)
; #define PG8_WAIT_V(n) asm volatile("s_waitcnt vmcnt(" #n ")" ::: "memory")
; #define PG8_WAIT_L(n) asm volatile("s_waitcnt lgkmcnt(" #n ")" ::: "memory")
; #define PG8_BAR __builtin_amdgcn_s_barrier()
; #define PG8_SCHED __builtin_amdgcn_sched_barrier(0)
; template <class Epi, class Sched, bool ALIGN_EPI = false, bool SP2 = false>
; __device__ __forceinline__ void gemm_phase(PG8_LAS unsigned char* lds, const Gemm g, const Sched& S, const Epi& E, const int tid) {
;     ...
;             const char* a2 = last ? nA : cA + (size_t)(t + 2) * kstep; const char* b2 = last ? nB : cB + (size_t)(t + 2) * kstep;
;             const char* a3 = a2 + kstep; const char* b3 = b2 + kstep;
;             if (last && has_next) S.a_ready(nxt);
;             if constexpr (SP2) {
;             PG8_LDB(B0, 0, 0); PG8_LDB(B1, 0, 1); PG8_SCHED; PG8_LDA(At, 0, 0); PG8_STAGE(PG8_SA(1, 1), a1 + hstep, voffA);
;             PG8_WAIT_V(8); PG8_WAIT_L(0); PG8_BAR; PG8_MMA(0, 0, At, B0); PG8_MMA(0, 1, At, B1); PG8_BAR; PG8_SCHED;
;             PG8_LDA(At, 0, 1); PG8_STAGE(PG8_SB(0, 0), b2, voffB); PG8_STAGE(PG8_SB(0, 1), b2 + hstep, voffB); PG8_STAGE(PG8_SA(0, 0), a2, voffA);
;             PG8_WAIT_V(8); PG8_WAIT_L(0); PG8_BAR; PG8_MMA(1, 0, At, B0); PG8_MMA(1, 1, At, B1); PG8_BAR; PG8_SCHED;
.LBB0_87:
	s_add_u32 s38, s22, s68
	s_addc_u32 s39, s23, s69
	s_add_u32 s38, s38, 0x100
	s_addc_u32 s39, s39, 0
	s_add_u32 s50, s89, s68
	s_addc_u32 s51, s90, s69
	s_add_i32 s92, 0, 0x10000
	s_cmpk_eq_i32 s68, 0x700
	s_cselect_b32 s73, s15, s39
	s_cselect_b32 s72, s86, s38
	v_add_u32_e32 v150, s92, v153
	s_cselect_b32 s71, s87, s51
	s_cselect_b32 s70, s88, s50
	s_add_i32 s38, 0, 0x14000
	ds_read_b128 v[170:173], v150
	ds_read_b128 v[174:177], v150 offset:1024
	ds_read_b128 v[178:181], v150 offset:2048
	ds_read_b128 v[182:185], v150 offset:3072
	v_add_u32_e32 v150, s38, v153
	ds_read_b128 v[186:189], v150
	ds_read_b128 v[190:193], v150 offset:1024
	ds_read_b128 v[206:209], v150 offset:2048
	ds_read_b128 v[210:213], v150 offset:3072
	v_lshl_add_u64 v[246:247], v[146:147], 0, s[68:69]
	s_add_i32 m0, s76, 0xc000
	ds_read_b128 v[214:217], v167
	ds_read_b128 v[218:221], v167 offset:1024
	ds_read_b128 v[222:225], v167 offset:2048
	ds_read_b128 v[226:229], v167 offset:3072
	ds_read_b128 v[230:233], v167 offset:4096
	ds_read_b128 v[234:237], v167 offset:5120
	ds_read_b128 v[238:241], v167 offset:6144
	ds_read_b128 v[242:245], v167 offset:7168
	global_load_lds_dwordx4 v[246:247], off
	v_lshl_add_u64 v[246:247], v[148:149], 0, s[68:69]
	s_add_i32 m0, s76, 0xe000
	s_nop 0
	global_load_lds_dwordx4 v[246:247], off
	s_waitcnt vmcnt(8)
	s_waitcnt lgkmcnt(0)
	s_setprio 1
	s_barrier
	v_mfma_f32_16x16x32_bf16 v[126:129], v[170:173], v[214:217], v[126:129]
	v_mfma_f32_16x16x32_bf16 v[122:125], v[178:181], v[214:217], v[122:125]
	v_mfma_f32_16x16x32_bf16 v[110:113], v[170:173], v[222:225], v[110:113]
	v_mfma_f32_16x16x32_bf16 v[106:109], v[178:181], v[222:225], v[106:109]
	v_mfma_f32_16x16x32_bf16 v[94:97], v[170:173], v[230:233], v[94:97]
	v_mfma_f32_16x16x32_bf16 v[90:93], v[178:181], v[230:233], v[90:93]
	v_mfma_f32_16x16x32_bf16 v[78:81], v[170:173], v[238:241], v[78:81]
	v_mfma_f32_16x16x32_bf16 v[74:77], v[178:181], v[238:241], v[74:77]
	v_mfma_f32_16x16x32_bf16 v[126:129], v[174:177], v[218:221], v[126:129]
	v_mfma_f32_16x16x32_bf16 v[122:125], v[182:185], v[218:221], v[122:125]
	v_mfma_f32_16x16x32_bf16 v[110:113], v[174:177], v[226:229], v[110:113]
	v_mfma_f32_16x16x32_bf16 v[106:109], v[182:185], v[226:229], v[106:109]
	v_mfma_f32_16x16x32_bf16 v[94:97], v[174:177], v[234:237], v[94:97]
	v_mfma_f32_16x16x32_bf16 v[90:93], v[182:185], v[234:237], v[90:93]
	v_mfma_f32_16x16x32_bf16 v[78:81], v[174:177], v[242:245], v[78:81]
	v_mfma_f32_16x16x32_bf16 v[74:77], v[182:185], v[242:245], v[74:77]
	v_mfma_f32_16x16x32_bf16 v[118:121], v[186:189], v[214:217], v[118:121]
	v_mfma_f32_16x16x32_bf16 v[114:117], v[206:209], v[214:217], v[114:117]
	v_mfma_f32_16x16x32_bf16 v[102:105], v[186:189], v[222:225], v[102:105]
	v_mfma_f32_16x16x32_bf16 v[98:101], v[206:209], v[222:225], v[98:101]
	v_mfma_f32_16x16x32_bf16 v[86:89], v[186:189], v[230:233], v[86:89]
	v_mfma_f32_16x16x32_bf16 v[82:85], v[206:209], v[230:233], v[82:85]
	v_mfma_f32_16x16x32_bf16 v[70:73], v[186:189], v[238:241], v[70:73]
	v_mfma_f32_16x16x32_bf16 v[66:69], v[206:209], v[238:241], v[66:69]
	v_mfma_f32_16x16x32_bf16 v[118:121], v[190:193], v[218:221], v[118:121]
	v_mfma_f32_16x16x32_bf16 v[114:117], v[210:213], v[218:221], v[114:117]
	v_mfma_f32_16x16x32_bf16 v[102:105], v[190:193], v[226:229], v[102:105]
	v_mfma_f32_16x16x32_bf16 v[98:101], v[210:213], v[226:229], v[98:101]
	s_barrier
	v_mfma_f32_16x16x32_bf16 v[86:89], v[190:193], v[234:237], v[86:89]
	v_mfma_f32_16x16x32_bf16 v[82:85], v[210:213], v[234:237], v[82:85]
	v_mfma_f32_16x16x32_bf16 v[70:73], v[190:193], v[242:245], v[70:73]
	v_mfma_f32_16x16x32_bf16 v[66:69], v[210:213], v[242:245], v[66:69]
	s_setprio 0
	s_add_i32 s39, s92, s75
	v_lshl_add_u64 v[246:247], s[70:71], 0, v[0:1]
	s_mov_b32 m0, s39
	ds_read_b128 v[214:217], v167 offset:16384
	ds_read_b128 v[218:221], v167 offset:17408
	ds_read_b128 v[222:225], v167 offset:18432
	ds_read_b128 v[226:229], v167 offset:19456
	ds_read_b128 v[230:233], v167 offset:20480
	ds_read_b128 v[234:237], v167 offset:21504
	ds_read_b128 v[238:241], v167 offset:22528
	ds_read_b128 v[242:245], v167 offset:23552
	global_load_lds_dwordx4 v[246:247], off
	s_add_i32 m0, s39, 0x2000
	s_add_u32 s50, s70, 0x40000
	v_lshl_add_u64 v[248:249], s[70:71], 0, v[130:131]
	s_addc_u32 s51, s71, 0
	s_add_i32 s38, s38, s75
	global_load_lds_dwordx4 v[248:249], off
	v_lshl_add_u64 v[250:251], s[50:51], 0, v[0:1]
	s_mov_b32 m0, s38
	v_lshl_add_u64 v[252:253], s[72:73], 0, v[132:133]
	global_load_lds_dwordx4 v[250:251], off
	v_lshl_add_u64 v[250:251], s[50:51], 0, v[130:131]
	s_add_i32 m0, s38, 0x2000
	s_nop 0
	global_load_lds_dwordx4 v[250:251], off
	v_lshl_add_u64 v[250:251], s[72:73], 0, v[134:135]
	s_mov_b32 m0, s76
	s_nop 0
	global_load_lds_dwordx4 v[250:251], off
	s_mov_b32 m0, s77
	s_nop 0
	global_load_lds_dwordx4 v[252:253], off
	s_waitcnt vmcnt(8)
	s_waitcnt lgkmcnt(0)
	s_setprio 1
	s_barrier
; #define PG8_STAGE(bufoff, gbase, voff) do { _Pragma("unroll") for (int _i = 0; _i < 2; ++_i) \
;         __builtin_amdgcn_global_load_lds((const unsigned*)((const char*)(gbase) + (voff)[_i]), (PG8_LAS unsigned*)(lds + (bufoff) + ldsw + _i * 8192), 16, 0, 0); } while (0)
; #define PG8_LDA(dst, b, h) do { _Pragma("unroll") for (int m = 0; m < 4; ++m) _Pragma("unroll") for (int k = 0; k < 2; ++k) dst[m][k] = *(const PG8_LAS bf16x8*)(lds + PG8_SA(b, h) + aoff + m * 2048 + k * 1024); } while (0)
; #define PG8_LDB(dst, b, h) do { _Pragma("unroll") for (int n = 0; n < 2; ++n) _Pragma("unroll") for (int k = 0; k < 2; ++k) dst[n][k] = *(const PG8_LAS bf16x8*)(lds + PG8_SB(b, h) + boff + n * 2048 + k * 1024); } while (0)
; #define PG8_MMA(ai, bj, At, Bt) do { __builtin_amdgcn_s_setprio(1); _Pragma("unroll") for (int m = 0; m < 4; ++m) _Pragma("unroll") for (int n = 0; n < 2; ++n) _Pragma("unroll") for (int k = 0; k < 2; ++k) \
;         acc[ai][bj][m][n] = __builtin_amdgcn_mfma_f32_16x16x32_bf16(Bt[n][k], At[m][k], acc[ai][bj][m][n], 0, 0, 0); __builtin_amdgcn_s_setprio(0); } while (0)
; #define PG8_WAIT_V(n) asm volatile("s_waitcnt vmcnt(" #n ")" ::: "memory")
; #define PG8_WAIT_L(n) asm volatile("s_waitcnt lgkmcnt(" #n ")" ::: "memory")
; #define PG8_BAR __builtin_amdgcn_s_barrier()
; #define PG8_SCHED __builtin_amdgcn_sched_barrier(0)
; template <class Epi, class Sched, bool ALIGN_EPI = false, bool SP2 = false>
; __device__ __forceinline__ void gemm_phase(PG8_LAS unsigned char* lds, const Gemm g, const Sched& S, const Epi& E, const int tid) {
;     ...
;             PG8_WAIT_V(8); PG8_WAIT_L(0); PG8_BAR; PG8_MMA(1, 0, At, B0); PG8_MMA(1, 1, At, B1); PG8_BAR; PG8_SCHED;
;             PG8_LDB(B0, 1, 0); PG8_LDB(B1, 1, 1); PG8_SCHED; PG8_LDA(At, 1, 0); PG8_STAGE(PG8_SA(0, 1), a2 + hstep, voffA);
;             PG8_WAIT_V(8); PG8_WAIT_L(0); PG8_BAR; PG8_MMA(0, 0, At, B0); PG8_MMA(0, 1, At, B1); PG8_BAR; PG8_SCHED;
	v_mfma_f32_16x16x32_bf16 v[62:65], v[170:173], v[214:217], v[62:65]
	v_mfma_f32_16x16x32_bf16 v[58:61], v[178:181], v[214:217], v[58:61]
	v_mfma_f32_16x16x32_bf16 v[46:49], v[170:173], v[222:225], v[46:49]
	v_mfma_f32_16x16x32_bf16 v[42:45], v[178:181], v[222:225], v[42:45]
	v_mfma_f32_16x16x32_bf16 v[30:33], v[170:173], v[230:233], v[30:33]
	v_mfma_f32_16x16x32_bf16 v[26:29], v[178:181], v[230:233], v[26:29]
	v_mfma_f32_16x16x32_bf16 v[14:17], v[170:173], v[238:241], v[14:17]
	v_mfma_f32_16x16x32_bf16 v[10:13], v[178:181], v[238:241], v[10:13]
	v_mfma_f32_16x16x32_bf16 v[62:65], v[174:177], v[218:221], v[62:65]
	v_mfma_f32_16x16x32_bf16 v[58:61], v[182:185], v[218:221], v[58:61]
	v_mfma_f32_16x16x32_bf16 v[46:49], v[174:177], v[226:229], v[46:49]
	v_mfma_f32_16x16x32_bf16 v[42:45], v[182:185], v[226:229], v[42:45]
	v_mfma_f32_16x16x32_bf16 v[30:33], v[174:177], v[234:237], v[30:33]
	v_mfma_f32_16x16x32_bf16 v[26:29], v[182:185], v[234:237], v[26:29]
	v_mfma_f32_16x16x32_bf16 v[14:17], v[174:177], v[242:245], v[14:17]
	v_mfma_f32_16x16x32_bf16 v[10:13], v[182:185], v[242:245], v[10:13]
	v_mfma_f32_16x16x32_bf16 v[54:57], v[186:189], v[214:217], v[54:57]
	v_mfma_f32_16x16x32_bf16 v[50:53], v[206:209], v[214:217], v[50:53]
	v_mfma_f32_16x16x32_bf16 v[38:41], v[186:189], v[222:225], v[38:41]
	v_mfma_f32_16x16x32_bf16 v[34:37], v[206:209], v[222:225], v[34:37]
	v_mfma_f32_16x16x32_bf16 v[22:25], v[186:189], v[230:233], v[22:25]
	v_mfma_f32_16x16x32_bf16 v[18:21], v[206:209], v[230:233], v[18:21]
	v_mfma_f32_16x16x32_bf16 v[6:9], v[186:189], v[238:241], v[6:9]
	v_mfma_f32_16x16x32_bf16 v[2:5], v[206:209], v[238:241], v[2:5]
	v_mfma_f32_16x16x32_bf16 v[54:57], v[190:193], v[218:221], v[54:57]
	v_mfma_f32_16x16x32_bf16 v[50:53], v[210:213], v[218:221], v[50:53]
	v_mfma_f32_16x16x32_bf16 v[38:41], v[190:193], v[226:229], v[38:41]
	v_mfma_f32_16x16x32_bf16 v[34:37], v[210:213], v[226:229], v[34:37]
	s_barrier
	v_mfma_f32_16x16x32_bf16 v[22:25], v[190:193], v[234:237], v[22:25]
	v_mfma_f32_16x16x32_bf16 v[18:21], v[210:213], v[234:237], v[18:21]
	v_mfma_f32_16x16x32_bf16 v[6:9], v[190:193], v[242:245], v[6:9]
	v_mfma_f32_16x16x32_bf16 v[2:5], v[210:213], v[242:245], v[2:5]
	s_setprio 0
	s_add_i32 s38, 0, 0x18000
	v_add_u32_e32 v150, s38, v153
	s_add_i32 s39, 0, 0x1c000
	ds_read_b128 v[170:173], v150
	ds_read_b128 v[174:177], v150 offset:1024
	ds_read_b128 v[178:181], v150 offset:2048
	ds_read_b128 v[182:185], v150 offset:3072
	v_add_u32_e32 v150, s39, v153
	ds_read_b128 v[186:189], v150
	ds_read_b128 v[190:193], v150 offset:1024
	ds_read_b128 v[206:209], v150 offset:2048
	ds_read_b128 v[210:213], v150 offset:3072
	s_add_u32 s50, s72, 0x40000
	s_addc_u32 s51, s73, 0
	s_mov_b32 m0, s78
	v_lshl_add_u64 v[194:195], s[50:51], 0, v[134:135]
	ds_read_b128 v[214:217], v167 offset:32768
	ds_read_b128 v[218:221], v167 offset:33792
	ds_read_b128 v[222:225], v167 offset:34816
	ds_read_b128 v[226:229], v167 offset:35840
	ds_read_b128 v[230:233], v167 offset:36864
	ds_read_b128 v[234:237], v167 offset:37888
	ds_read_b128 v[238:241], v167 offset:38912
	ds_read_b128 v[242:245], v167 offset:39936
	global_load_lds_dwordx4 v[194:195], off
	v_lshl_add_u64 v[194:195], s[50:51], 0, v[132:133]
	s_mov_b32 m0, s79
	s_nop 0
	global_load_lds_dwordx4 v[194:195], off
	s_waitcnt vmcnt(8)
	s_waitcnt lgkmcnt(0)
	s_setprio 1
	s_barrier
	v_mfma_f32_16x16x32_bf16 v[126:129], v[170:173], v[214:217], v[126:129]
	v_mfma_f32_16x16x32_bf16 v[122:125], v[178:181], v[214:217], v[122:125]
	v_mfma_f32_16x16x32_bf16 v[110:113], v[170:173], v[222:225], v[110:113]
	v_mfma_f32_16x16x32_bf16 v[106:109], v[178:181], v[222:225], v[106:109]
	v_mfma_f32_16x16x32_bf16 v[94:97], v[170:173], v[230:233], v[94:97]
	v_mfma_f32_16x16x32_bf16 v[90:93], v[178:181], v[230:233], v[90:93]
	v_mfma_f32_16x16x32_bf16 v[78:81], v[170:173], v[238:241], v[78:81]
	v_mfma_f32_16x16x32_bf16 v[74:77], v[178:181], v[238:241], v[74:77]
	v_mfma_f32_16x16x32_bf16 v[126:129], v[174:177], v[218:221], v[126:129]
	v_mfma_f32_16x16x32_bf16 v[122:125], v[182:185], v[218:221], v[122:125]
	v_mfma_f32_16x16x32_bf16 v[110:113], v[174:177], v[226:229], v[110:113]
	v_mfma_f32_16x16x32_bf16 v[106:109], v[182:185], v[226:229], v[106:109]
	v_mfma_f32_16x16x32_bf16 v[94:97], v[174:177], v[234:237], v[94:97]
	v_mfma_f32_16x16x32_bf16 v[90:93], v[182:185], v[234:237], v[90:93]
	v_mfma_f32_16x16x32_bf16 v[78:81], v[174:177], v[242:245], v[78:81]
	v_mfma_f32_16x16x32_bf16 v[74:77], v[182:185], v[242:245], v[74:77]
	v_mfma_f32_16x16x32_bf16 v[118:121], v[186:189], v[214:217], v[118:121]
	v_mfma_f32_16x16x32_bf16 v[114:117], v[206:209], v[214:217], v[114:117]
	v_mfma_f32_16x16x32_bf16 v[102:105], v[186:189], v[222:225], v[102:105]
	v_mfma_f32_16x16x32_bf16 v[98:101], v[206:209], v[222:225], v[98:101]
	v_mfma_f32_16x16x32_bf16 v[86:89], v[186:189], v[230:233], v[86:89]
	v_mfma_f32_16x16x32_bf16 v[82:85], v[206:209], v[230:233], v[82:85]
	v_mfma_f32_16x16x32_bf16 v[70:73], v[186:189], v[238:241], v[70:73]
	v_mfma_f32_16x16x32_bf16 v[66:69], v[206:209], v[238:241], v[66:69]
	v_mfma_f32_16x16x32_bf16 v[118:121], v[190:193], v[218:221], v[118:121]
	v_mfma_f32_16x16x32_bf16 v[114:117], v[210:213], v[218:221], v[114:117]
	v_mfma_f32_16x16x32_bf16 v[102:105], v[190:193], v[226:229], v[102:105]
	v_mfma_f32_16x16x32_bf16 v[98:101], v[210:213], v[226:229], v[98:101]
	s_barrier
; #define PG8_STAGE(bufoff, gbase, voff) do { _Pragma("unroll") for (int _i = 0; _i < 2; ++_i) \
;         __builtin_amdgcn_global_load_lds((const unsigned*)((const char*)(gbase) + (voff)[_i]), (PG8_LAS unsigned*)(lds + (bufoff) + ldsw + _i * 8192), 16, 0, 0); } while (0)
; #define PG8_LDA(dst, b, h) do { _Pragma("unroll") for (int m = 0; m < 4; ++m) _Pragma("unroll") for (int k = 0; k < 2; ++k) dst[m][k] = *(const PG8_LAS bf16x8*)(lds + PG8_SA(b, h) + aoff + m * 2048 + k * 1024); } while (0)
; #define PG8_MMA(ai, bj, At, Bt) do { __builtin_amdgcn_s_setprio(1); _Pragma("unroll") for (int m = 0; m < 4; ++m) _Pragma("unroll") for (int n = 0; n < 2; ++n) _Pragma("unroll") for (int k = 0; k < 2; ++k) \
;         acc[ai][bj][m][n] = __builtin_amdgcn_mfma_f32_16x16x32_bf16(Bt[n][k], At[m][k], acc[ai][bj][m][n], 0, 0, 0); __builtin_amdgcn_s_setprio(0); } while (0)
; #define PG8_WAIT_V(n) asm volatile("s_waitcnt vmcnt(" #n ")" ::: "memory")
; #define PG8_WAIT_L(n) asm volatile("s_waitcnt lgkmcnt(" #n ")" ::: "memory")
; #define PG8_BAR __builtin_amdgcn_s_barrier()
; #define PG8_SCHED __builtin_amdgcn_sched_barrier(0)
; template <class Epi, class Sched, bool ALIGN_EPI = false, bool SP2 = false>
; __device__ __forceinline__ void gemm_phase(PG8_LAS unsigned char* lds, const Gemm g, const Sched& S, const Epi& E, const int tid) {
;     ...
;             PG8_WAIT_V(8); PG8_WAIT_L(0); PG8_BAR; PG8_MMA(0, 0, At, B0); PG8_MMA(0, 1, At, B1); PG8_BAR; PG8_SCHED;
;             PG8_LDA(At, 1, 1); PG8_STAGE(PG8_SB(1, 0), b3, voffB); PG8_STAGE(PG8_SB(1, 1), b3 + hstep, voffB); PG8_STAGE(PG8_SA(1, 0), a3, voffA);
;             PG8_WAIT_V(8); PG8_WAIT_L(0); PG8_BAR; PG8_MMA(1, 0, At, B0); PG8_MMA(1, 1, At, B1); PG8_BAR; PG8_SCHED;
	v_mfma_f32_16x16x32_bf16 v[86:89], v[190:193], v[234:237], v[86:89]
	v_mfma_f32_16x16x32_bf16 v[82:85], v[210:213], v[234:237], v[82:85]
	v_mfma_f32_16x16x32_bf16 v[70:73], v[190:193], v[242:245], v[70:73]
	v_mfma_f32_16x16x32_bf16 v[66:69], v[210:213], v[242:245], v[66:69]
	s_setprio 0
	s_add_i32 s38, s38, s75
	v_lshl_add_u64 v[194:195], v[246:247], 0, s[56:57]
	s_mov_b32 m0, s38
	ds_read_b128 v[214:217], v167 offset:49152
	ds_read_b128 v[218:221], v167 offset:50176
	ds_read_b128 v[222:225], v167 offset:51200
	ds_read_b128 v[226:229], v167 offset:52224
	ds_read_b128 v[230:233], v167 offset:53248
	ds_read_b128 v[234:237], v167 offset:54272
	ds_read_b128 v[238:241], v167 offset:55296
	ds_read_b128 v[242:245], v167 offset:56320
	global_load_lds_dwordx4 v[194:195], off
	s_add_i32 m0, s38, 0x2000
	s_add_u32 s50, s70, 0x40080
	v_lshl_add_u64 v[194:195], v[248:249], 0, s[56:57]
	s_addc_u32 s51, s71, 0
	s_add_i32 s38, s39, s75
	global_load_lds_dwordx4 v[194:195], off
	v_lshl_add_u64 v[194:195], s[50:51], 0, v[0:1]
	s_mov_b32 m0, s38
	s_nop 0
	global_load_lds_dwordx4 v[194:195], off
	v_lshl_add_u64 v[194:195], s[50:51], 0, v[130:131]
	s_add_i32 m0, s38, 0x2000
	s_nop 0
	global_load_lds_dwordx4 v[194:195], off
	v_lshl_add_u64 v[194:195], v[250:251], 0, s[56:57]
	s_mov_b32 m0, s80
	s_nop 0
	global_load_lds_dwordx4 v[194:195], off
	v_lshl_add_u64 v[194:195], v[252:253], 0, s[56:57]
	s_mov_b32 m0, s81
	s_nop 0
	global_load_lds_dwordx4 v[194:195], off
	s_waitcnt vmcnt(8)
	s_waitcnt lgkmcnt(0)
	s_setprio 1
	s_barrier
	v_mfma_f32_16x16x32_bf16 v[62:65], v[170:173], v[214:217], v[62:65]
	v_mfma_f32_16x16x32_bf16 v[58:61], v[178:181], v[214:217], v[58:61]
	v_mfma_f32_16x16x32_bf16 v[46:49], v[170:173], v[222:225], v[46:49]
	v_mfma_f32_16x16x32_bf16 v[42:45], v[178:181], v[222:225], v[42:45]
	v_mfma_f32_16x16x32_bf16 v[30:33], v[170:173], v[230:233], v[30:33]
	v_mfma_f32_16x16x32_bf16 v[26:29], v[178:181], v[230:233], v[26:29]
	v_mfma_f32_16x16x32_bf16 v[14:17], v[170:173], v[238:241], v[14:17]
	v_mfma_f32_16x16x32_bf16 v[10:13], v[178:181], v[238:241], v[10:13]
	v_mfma_f32_16x16x32_bf16 v[62:65], v[174:177], v[218:221], v[62:65]
	v_mfma_f32_16x16x32_bf16 v[58:61], v[182:185], v[218:221], v[58:61]
	v_mfma_f32_16x16x32_bf16 v[46:49], v[174:177], v[226:229], v[46:49]
	v_mfma_f32_16x16x32_bf16 v[42:45], v[182:185], v[226:229], v[42:45]
	v_mfma_f32_16x16x32_bf16 v[30:33], v[174:177], v[234:237], v[30:33]
	v_mfma_f32_16x16x32_bf16 v[26:29], v[182:185], v[234:237], v[26:29]
	v_mfma_f32_16x16x32_bf16 v[14:17], v[174:177], v[242:245], v[14:17]
	v_mfma_f32_16x16x32_bf16 v[10:13], v[182:185], v[242:245], v[10:13]
	v_mfma_f32_16x16x32_bf16 v[54:57], v[186:189], v[214:217], v[54:57]
	v_mfma_f32_16x16x32_bf16 v[50:53], v[206:209], v[214:217], v[50:53]
	v_mfma_f32_16x16x32_bf16 v[38:41], v[186:189], v[222:225], v[38:41]
	v_mfma_f32_16x16x32_bf16 v[34:37], v[206:209], v[222:225], v[34:37]
	v_mfma_f32_16x16x32_bf16 v[22:25], v[186:189], v[230:233], v[22:25]
	v_mfma_f32_16x16x32_bf16 v[18:21], v[206:209], v[230:233], v[18:21]
	v_mfma_f32_16x16x32_bf16 v[6:9], v[186:189], v[238:241], v[6:9]
	v_mfma_f32_16x16x32_bf16 v[2:5], v[206:209], v[238:241], v[2:5]
	v_mfma_f32_16x16x32_bf16 v[54:57], v[190:193], v[218:221], v[54:57]
	v_mfma_f32_16x16x32_bf16 v[50:53], v[210:213], v[218:221], v[50:53]
	v_mfma_f32_16x16x32_bf16 v[38:41], v[190:193], v[226:229], v[38:41]
	v_mfma_f32_16x16x32_bf16 v[34:37], v[210:213], v[226:229], v[34:37]
	s_barrier
	v_mfma_f32_16x16x32_bf16 v[22:25], v[190:193], v[234:237], v[22:25]
	v_mfma_f32_16x16x32_bf16 v[18:21], v[210:213], v[234:237], v[18:21]
	v_mfma_f32_16x16x32_bf16 v[6:9], v[190:193], v[242:245], v[6:9]
	v_mfma_f32_16x16x32_bf16 v[2:5], v[210:213], v[242:245], v[2:5]
	s_setprio 0
	s_add_i32 s91, s91, 2
	s_add_u32 s68, s68, 0x100
	s_addc_u32 s69, s69, 0
	s_cmp_gt_u32 s91, 13
	s_cbranch_scc1 .LBB0_90

; #define PG8_STAGE(bufoff, gbase, voff) do { _Pragma("unroll") for (int _i = 0; _i < 2; ++_i) \
;         __builtin_amdgcn_global_load_lds((const unsigned*)((const char*)(gbase) + (voff)[_i]), (PG8_LAS unsigned*)(lds + (bufoff) + ldsw + _i * 8192), 16, 0, 0); } while (0)
; #define PG8_LDA(dst, b, h) do { _Pragma("unroll") for (int m = 0; m < 4; ++m) _Pragma("unroll") for (int k = 0; k < 2; ++k) dst[m][k] = *(const PG8_LAS bf16x8*)(lds + PG8_SA(b, h) + aoff + m * 2048 + k * 1024); } while (0)
; #define PG8_LDB(dst, b, h) do { _Pragma("unroll") for (int n = 0; n < 2; ++n) _Pragma("unroll") for (int k = 0; k < 2; ++k) dst[n][k] = *(const PG8_LAS bf16x8*)(lds + PG8_SB(b, h) + boff + n * 2048 + k * 1024); } while (0)
; #define PG8_MMA(ai, bj, At, Bt) do { __builtin_amdgcn_s_setprio(1); _Pragma("unroll") for (int m = 0; m < 4; ++m) _Pragma("unroll") for (int n = 0; n < 2; ++n) _Pragma("unroll") for (int k = 0; k < 2; ++k) \
;         acc[ai][bj][m][n] = __builtin_amdgcn_mfma_f32_16x16x32_bf16(Bt[n][k], At[m][k], acc[ai][bj][m][n], 0, 0, 0); __builtin_amdgcn_s_setprio(0); } while (0)
; #define PG8_WAIT_V(n) asm volatile("s_waitcnt vmcnt(" #n ")" ::: "memory")
; #define PG8_WAIT_L(n) asm volatile("s_waitcnt lgkmcnt(" #n ")" ::: "memory")
; #define PG8_BAR __builtin_amdgcn_s_barrier()
; #define PG8_SCHED __builtin_amdgcn_sched_barrier(0)
; template <class Epi, class Sched, bool ALIGN_EPI = false, bool SP2 = false>
; __device__ __forceinline__ void gemm_phase(PG8_LAS unsigned char* lds, const Gemm g, const Sched& S, const Epi& E, const int tid) {
;     ...
;             const char* a2 = last ? nA : cA + (size_t)(t + 2) * kstep; const char* b2 = last ? nB : cB + (size_t)(t + 2) * kstep;
;             const char* a3 = a2 + kstep; const char* b3 = b2 + kstep;
;             if (last && has_next) S.a_ready(nxt);
;             if constexpr (SP2) {
;             PG8_LDB(B0, 0, 0); PG8_LDB(B1, 0, 1); PG8_SCHED; PG8_LDA(At, 0, 0); PG8_STAGE(PG8_SA(1, 1), a1 + hstep, voffA);
;             PG8_WAIT_V(8); PG8_WAIT_L(0); PG8_BAR; PG8_MMA(0, 0, At, B0); PG8_MMA(0, 1, At, B1); PG8_BAR; PG8_SCHED;
;             PG8_LDA(At, 0, 1); PG8_STAGE(PG8_SB(0, 0), b2, voffB); PG8_STAGE(PG8_SB(0, 1), b2 + hstep, voffB); PG8_STAGE(PG8_SA(0, 0), a2, voffA);
;             PG8_WAIT_V(8); PG8_WAIT_L(0); PG8_BAR; PG8_MMA(1, 0, At, B0); PG8_MMA(1, 1, At, B1); PG8_BAR; PG8_SCHED;
.LBB0_208:
	s_add_u32 s38, s10, s12
	s_addc_u32 s39, s11, s13
	s_add_u32 s38, s38, 0x100
	s_addc_u32 s39, s39, 0
	s_add_u32 s51, vcc_lo, s12
	s_addc_u32 s74, vcc_hi, s13
	s_add_i32 s59, 0, 0x10000
	s_cmpk_eq_i32 s12, 0x700
	s_cselect_b32 s77, s49, s39
	s_cselect_b32 s76, s78, s38
	v_add_u32_e32 v0, s59, v153
	s_cselect_b32 s75, s69, s74
	s_cselect_b32 s74, s79, s51
	s_add_i32 s51, 0, 0x14000
	ds_read_b128 v[170:173], v0
	ds_read_b128 v[174:177], v0 offset:1024
	ds_read_b128 v[178:181], v0 offset:2048
	ds_read_b128 v[182:185], v0 offset:3072
	v_add_u32_e32 v0, s51, v153
	ds_read_b128 v[186:189], v0
	ds_read_b128 v[190:193], v0 offset:1024
	ds_read_b128 v[206:209], v0 offset:2048
	ds_read_b128 v[210:213], v0 offset:3072
	v_lshl_add_u64 v[194:195], v[148:149], 0, s[12:13]
	s_add_i32 m0, s84, 0xc000
	ds_read_b128 v[214:217], v167
	ds_read_b128 v[218:221], v167 offset:1024
	ds_read_b128 v[222:225], v167 offset:2048
	ds_read_b128 v[226:229], v167 offset:3072
	ds_read_b128 v[230:233], v167 offset:4096
	ds_read_b128 v[234:237], v167 offset:5120
	ds_read_b128 v[238:241], v167 offset:6144
	ds_read_b128 v[242:245], v167 offset:7168
	global_load_lds_dwordx4 v[194:195], off
	v_lshl_add_u64 v[194:195], v[150:151], 0, s[12:13]
	s_add_i32 m0, s84, 0xe000
	s_nop 0
	global_load_lds_dwordx4 v[194:195], off
	s_waitcnt vmcnt(8)
	s_waitcnt lgkmcnt(0)
	s_setprio 1
	s_barrier
	v_mfma_f32_16x16x32_bf16 v[126:129], v[170:173], v[214:217], v[126:129]
	v_mfma_f32_16x16x32_bf16 v[122:125], v[178:181], v[214:217], v[122:125]
	v_mfma_f32_16x16x32_bf16 v[110:113], v[170:173], v[222:225], v[110:113]
	v_mfma_f32_16x16x32_bf16 v[106:109], v[178:181], v[222:225], v[106:109]
	v_mfma_f32_16x16x32_bf16 v[94:97], v[170:173], v[230:233], v[94:97]
	v_mfma_f32_16x16x32_bf16 v[90:93], v[178:181], v[230:233], v[90:93]
	v_mfma_f32_16x16x32_bf16 v[78:81], v[170:173], v[238:241], v[78:81]
	v_mfma_f32_16x16x32_bf16 v[74:77], v[178:181], v[238:241], v[74:77]
	v_mfma_f32_16x16x32_bf16 v[126:129], v[174:177], v[218:221], v[126:129]
	v_mfma_f32_16x16x32_bf16 v[122:125], v[182:185], v[218:221], v[122:125]
	v_mfma_f32_16x16x32_bf16 v[110:113], v[174:177], v[226:229], v[110:113]
	v_mfma_f32_16x16x32_bf16 v[106:109], v[182:185], v[226:229], v[106:109]
	v_mfma_f32_16x16x32_bf16 v[94:97], v[174:177], v[234:237], v[94:97]
	v_mfma_f32_16x16x32_bf16 v[90:93], v[182:185], v[234:237], v[90:93]
	v_mfma_f32_16x16x32_bf16 v[78:81], v[174:177], v[242:245], v[78:81]
	v_mfma_f32_16x16x32_bf16 v[74:77], v[182:185], v[242:245], v[74:77]
	v_mfma_f32_16x16x32_bf16 v[118:121], v[186:189], v[214:217], v[118:121]
	v_mfma_f32_16x16x32_bf16 v[114:117], v[206:209], v[214:217], v[114:117]
	v_mfma_f32_16x16x32_bf16 v[102:105], v[186:189], v[222:225], v[102:105]
	v_mfma_f32_16x16x32_bf16 v[98:101], v[206:209], v[222:225], v[98:101]
	v_mfma_f32_16x16x32_bf16 v[86:89], v[186:189], v[230:233], v[86:89]
	v_mfma_f32_16x16x32_bf16 v[82:85], v[206:209], v[230:233], v[82:85]
	v_mfma_f32_16x16x32_bf16 v[70:73], v[186:189], v[238:241], v[70:73]
	v_mfma_f32_16x16x32_bf16 v[66:69], v[206:209], v[238:241], v[66:69]
	v_mfma_f32_16x16x32_bf16 v[118:121], v[190:193], v[218:221], v[118:121]
	v_mfma_f32_16x16x32_bf16 v[114:117], v[210:213], v[218:221], v[114:117]
	v_mfma_f32_16x16x32_bf16 v[102:105], v[190:193], v[226:229], v[102:105]
	v_mfma_f32_16x16x32_bf16 v[98:101], v[210:213], v[226:229], v[98:101]
	s_barrier
	v_mfma_f32_16x16x32_bf16 v[86:89], v[190:193], v[234:237], v[86:89]
	v_mfma_f32_16x16x32_bf16 v[82:85], v[210:213], v[234:237], v[82:85]
	v_mfma_f32_16x16x32_bf16 v[70:73], v[190:193], v[242:245], v[70:73]
	v_mfma_f32_16x16x32_bf16 v[66:69], v[210:213], v[242:245], v[66:69]
	s_setprio 0
	s_add_i32 s38, s59, s83
	v_lshl_add_u64 v[194:195], s[74:75], 0, v[134:135]
	s_mov_b32 m0, s38
	ds_read_b128 v[214:217], v167 offset:16384
	ds_read_b128 v[218:221], v167 offset:17408
	ds_read_b128 v[222:225], v167 offset:18432
	ds_read_b128 v[226:229], v167 offset:19456
	ds_read_b128 v[230:233], v167 offset:20480
	ds_read_b128 v[234:237], v167 offset:21504
	ds_read_b128 v[238:241], v167 offset:22528
	ds_read_b128 v[242:245], v167 offset:23552
	global_load_lds_dwordx4 v[194:195], off
	s_add_i32 m0, s38, 0x2000
	s_add_u32 s38, s74, 0x40000
	v_lshl_add_u64 v[246:247], s[74:75], 0, v[130:131]
	s_addc_u32 s39, s75, 0
	s_add_i32 s51, s51, s83
	global_load_lds_dwordx4 v[246:247], off
	v_lshl_add_u64 v[248:249], s[38:39], 0, v[134:135]
	s_mov_b32 m0, s51
	v_lshl_add_u64 v[250:251], s[76:77], 0, v[132:133]
	global_load_lds_dwordx4 v[248:249], off
	v_lshl_add_u64 v[248:249], s[38:39], 0, v[130:131]
	s_add_i32 m0, s51, 0x2000
	s_nop 0
	global_load_lds_dwordx4 v[248:249], off
	v_lshl_add_u64 v[248:249], s[76:77], 0, v[136:137]
	s_mov_b32 m0, s84
	s_nop 0
	global_load_lds_dwordx4 v[248:249], off
	s_mov_b32 m0, s85
	s_nop 0
	global_load_lds_dwordx4 v[250:251], off
	s_waitcnt vmcnt(8)
	s_waitcnt lgkmcnt(0)
	s_setprio 1
	s_barrier
; #define PG8_STAGE(bufoff, gbase, voff) do { _Pragma("unroll") for (int _i = 0; _i < 2; ++_i) \
;         __builtin_amdgcn_global_load_lds((const unsigned*)((const char*)(gbase) + (voff)[_i]), (PG8_LAS unsigned*)(lds + (bufoff) + ldsw + _i * 8192), 16, 0, 0); } while (0)
; #define PG8_LDA(dst, b, h) do { _Pragma("unroll") for (int m = 0; m < 4; ++m) _Pragma("unroll") for (int k = 0; k < 2; ++k) dst[m][k] = *(const PG8_LAS bf16x8*)(lds + PG8_SA(b, h) + aoff + m * 2048 + k * 1024); } while (0)
; #define PG8_LDB(dst, b, h) do { _Pragma("unroll") for (int n = 0; n < 2; ++n) _Pragma("unroll") for (int k = 0; k < 2; ++k) dst[n][k] = *(const PG8_LAS bf16x8*)(lds + PG8_SB(b, h) + boff + n * 2048 + k * 1024); } while (0)
; #define PG8_MMA(ai, bj, At, Bt) do { __builtin_amdgcn_s_setprio(1); _Pragma("unroll") for (int m = 0; m < 4; ++m) _Pragma("unroll") for (int n = 0; n < 2; ++n) _Pragma("unroll") for (int k = 0; k < 2; ++k) \
;         acc[ai][bj][m][n] = __builtin_amdgcn_mfma_f32_16x16x32_bf16(Bt[n][k], At[m][k], acc[ai][bj][m][n], 0, 0, 0); __builtin_amdgcn_s_setprio(0); } while (0)
; #define PG8_WAIT_V(n) asm volatile("s_waitcnt vmcnt(" #n ")" ::: "memory")
; #define PG8_WAIT_L(n) asm volatile("s_waitcnt lgkmcnt(" #n ")" ::: "memory")
; #define PG8_BAR __builtin_amdgcn_s_barrier()
; #define PG8_SCHED __builtin_amdgcn_sched_barrier(0)
; template <class Epi, class Sched, bool ALIGN_EPI = false, bool SP2 = false>
; __device__ __forceinline__ void gemm_phase(PG8_LAS unsigned char* lds, const Gemm g, const Sched& S, const Epi& E, const int tid) {
;     ...
;             PG8_WAIT_V(8); PG8_WAIT_L(0); PG8_BAR; PG8_MMA(1, 0, At, B0); PG8_MMA(1, 1, At, B1); PG8_BAR; PG8_SCHED;
;             PG8_LDB(B0, 1, 0); PG8_LDB(B1, 1, 1); PG8_SCHED; PG8_LDA(At, 1, 0); PG8_STAGE(PG8_SA(0, 1), a2 + hstep, voffA);
;             PG8_WAIT_V(8); PG8_WAIT_L(0); PG8_BAR; PG8_MMA(0, 0, At, B0); PG8_MMA(0, 1, At, B1); PG8_BAR; PG8_SCHED;
	v_mfma_f32_16x16x32_bf16 v[62:65], v[170:173], v[214:217], v[62:65]
	v_mfma_f32_16x16x32_bf16 v[58:61], v[178:181], v[214:217], v[58:61]
	v_mfma_f32_16x16x32_bf16 v[46:49], v[170:173], v[222:225], v[46:49]
	v_mfma_f32_16x16x32_bf16 v[42:45], v[178:181], v[222:225], v[42:45]
	v_mfma_f32_16x16x32_bf16 v[30:33], v[170:173], v[230:233], v[30:33]
	v_mfma_f32_16x16x32_bf16 v[26:29], v[178:181], v[230:233], v[26:29]
	v_mfma_f32_16x16x32_bf16 v[14:17], v[170:173], v[238:241], v[14:17]
	v_mfma_f32_16x16x32_bf16 v[10:13], v[178:181], v[238:241], v[10:13]
	v_mfma_f32_16x16x32_bf16 v[62:65], v[174:177], v[218:221], v[62:65]
	v_mfma_f32_16x16x32_bf16 v[58:61], v[182:185], v[218:221], v[58:61]
	v_mfma_f32_16x16x32_bf16 v[46:49], v[174:177], v[226:229], v[46:49]
	v_mfma_f32_16x16x32_bf16 v[42:45], v[182:185], v[226:229], v[42:45]
	v_mfma_f32_16x16x32_bf16 v[30:33], v[174:177], v[234:237], v[30:33]
	v_mfma_f32_16x16x32_bf16 v[26:29], v[182:185], v[234:237], v[26:29]
	v_mfma_f32_16x16x32_bf16 v[14:17], v[174:177], v[242:245], v[14:17]
	v_mfma_f32_16x16x32_bf16 v[10:13], v[182:185], v[242:245], v[10:13]
	v_mfma_f32_16x16x32_bf16 v[54:57], v[186:189], v[214:217], v[54:57]
	v_mfma_f32_16x16x32_bf16 v[50:53], v[206:209], v[214:217], v[50:53]
	v_mfma_f32_16x16x32_bf16 v[38:41], v[186:189], v[222:225], v[38:41]
	v_mfma_f32_16x16x32_bf16 v[34:37], v[206:209], v[222:225], v[34:37]
	v_mfma_f32_16x16x32_bf16 v[22:25], v[186:189], v[230:233], v[22:25]
	v_mfma_f32_16x16x32_bf16 v[18:21], v[206:209], v[230:233], v[18:21]
	v_mfma_f32_16x16x32_bf16 v[6:9], v[186:189], v[238:241], v[6:9]
	v_mfma_f32_16x16x32_bf16 v[2:5], v[206:209], v[238:241], v[2:5]
	v_mfma_f32_16x16x32_bf16 v[54:57], v[190:193], v[218:221], v[54:57]
	v_mfma_f32_16x16x32_bf16 v[50:53], v[210:213], v[218:221], v[50:53]
	v_mfma_f32_16x16x32_bf16 v[38:41], v[190:193], v[226:229], v[38:41]
	v_mfma_f32_16x16x32_bf16 v[34:37], v[210:213], v[226:229], v[34:37]
	s_barrier
	v_mfma_f32_16x16x32_bf16 v[22:25], v[190:193], v[234:237], v[22:25]
	v_mfma_f32_16x16x32_bf16 v[18:21], v[210:213], v[234:237], v[18:21]
	v_mfma_f32_16x16x32_bf16 v[6:9], v[190:193], v[242:245], v[6:9]
	v_mfma_f32_16x16x32_bf16 v[2:5], v[210:213], v[242:245], v[2:5]
	s_setprio 0
	s_add_i32 s51, 0, 0x18000
	v_add_u32_e32 v0, s51, v153
	s_add_i32 s59, 0, 0x1c000
	ds_read_b128 v[170:173], v0
	ds_read_b128 v[174:177], v0 offset:1024
	ds_read_b128 v[178:181], v0 offset:2048
	ds_read_b128 v[182:185], v0 offset:3072
	v_add_u32_e32 v0, s59, v153
	ds_read_b128 v[186:189], v0
	ds_read_b128 v[190:193], v0 offset:1024
	ds_read_b128 v[206:209], v0 offset:2048
	ds_read_b128 v[210:213], v0 offset:3072
	s_add_u32 s38, s76, 0x40000
	s_addc_u32 s39, s77, 0
	s_mov_b32 m0, s86
	v_lshl_add_u64 v[252:253], s[38:39], 0, v[136:137]
	ds_read_b128 v[214:217], v167 offset:32768
	ds_read_b128 v[218:221], v167 offset:33792
	ds_read_b128 v[222:225], v167 offset:34816
	ds_read_b128 v[226:229], v167 offset:35840
	ds_read_b128 v[230:233], v167 offset:36864
	ds_read_b128 v[234:237], v167 offset:37888
	ds_read_b128 v[238:241], v167 offset:38912
	ds_read_b128 v[242:245], v167 offset:39936
	global_load_lds_dwordx4 v[252:253], off
	v_lshl_add_u64 v[252:253], s[38:39], 0, v[132:133]
	s_mov_b32 m0, s87
	s_nop 0
	global_load_lds_dwordx4 v[252:253], off
	s_waitcnt vmcnt(8)
	s_waitcnt lgkmcnt(0)
	s_setprio 1
	s_barrier
	v_mfma_f32_16x16x32_bf16 v[126:129], v[170:173], v[214:217], v[126:129]
	v_mfma_f32_16x16x32_bf16 v[122:125], v[178:181], v[214:217], v[122:125]
	v_mfma_f32_16x16x32_bf16 v[110:113], v[170:173], v[222:225], v[110:113]
	v_mfma_f32_16x16x32_bf16 v[106:109], v[178:181], v[222:225], v[106:109]
	v_mfma_f32_16x16x32_bf16 v[94:97], v[170:173], v[230:233], v[94:97]
	v_mfma_f32_16x16x32_bf16 v[90:93], v[178:181], v[230:233], v[90:93]
	v_mfma_f32_16x16x32_bf16 v[78:81], v[170:173], v[238:241], v[78:81]
	v_mfma_f32_16x16x32_bf16 v[74:77], v[178:181], v[238:241], v[74:77]
	v_mfma_f32_16x16x32_bf16 v[126:129], v[174:177], v[218:221], v[126:129]
	v_mfma_f32_16x16x32_bf16 v[122:125], v[182:185], v[218:221], v[122:125]
	v_mfma_f32_16x16x32_bf16 v[110:113], v[174:177], v[226:229], v[110:113]
	v_mfma_f32_16x16x32_bf16 v[106:109], v[182:185], v[226:229], v[106:109]
	v_mfma_f32_16x16x32_bf16 v[94:97], v[174:177], v[234:237], v[94:97]
	v_mfma_f32_16x16x32_bf16 v[90:93], v[182:185], v[234:237], v[90:93]
	v_mfma_f32_16x16x32_bf16 v[78:81], v[174:177], v[242:245], v[78:81]
	v_mfma_f32_16x16x32_bf16 v[74:77], v[182:185], v[242:245], v[74:77]
	v_mfma_f32_16x16x32_bf16 v[118:121], v[186:189], v[214:217], v[118:121]
	v_mfma_f32_16x16x32_bf16 v[114:117], v[206:209], v[214:217], v[114:117]
	v_mfma_f32_16x16x32_bf16 v[102:105], v[186:189], v[222:225], v[102:105]
	v_mfma_f32_16x16x32_bf16 v[98:101], v[206:209], v[222:225], v[98:101]
	v_mfma_f32_16x16x32_bf16 v[86:89], v[186:189], v[230:233], v[86:89]
	v_mfma_f32_16x16x32_bf16 v[82:85], v[206:209], v[230:233], v[82:85]
	v_mfma_f32_16x16x32_bf16 v[70:73], v[186:189], v[238:241], v[70:73]
	v_mfma_f32_16x16x32_bf16 v[66:69], v[206:209], v[238:241], v[66:69]
	v_mfma_f32_16x16x32_bf16 v[118:121], v[190:193], v[218:221], v[118:121]
	v_mfma_f32_16x16x32_bf16 v[114:117], v[210:213], v[218:221], v[114:117]
	v_mfma_f32_16x16x32_bf16 v[102:105], v[190:193], v[226:229], v[102:105]
	v_mfma_f32_16x16x32_bf16 v[98:101], v[210:213], v[226:229], v[98:101]
	s_barrier
; #define PG8_STAGE(bufoff, gbase, voff) do { _Pragma("unroll") for (int _i = 0; _i < 2; ++_i) \
;         __builtin_amdgcn_global_load_lds((const unsigned*)((const char*)(gbase) + (voff)[_i]), (PG8_LAS unsigned*)(lds + (bufoff) + ldsw + _i * 8192), 16, 0, 0); } while (0)
; #define PG8_LDA(dst, b, h) do { _Pragma("unroll") for (int m = 0; m < 4; ++m) _Pragma("unroll") for (int k = 0; k < 2; ++k) dst[m][k] = *(const PG8_LAS bf16x8*)(lds + PG8_SA(b, h) + aoff + m * 2048 + k * 1024); } while (0)
; #define PG8_MMA(ai, bj, At, Bt) do { __builtin_amdgcn_s_setprio(1); _Pragma("unroll") for (int m = 0; m < 4; ++m) _Pragma("unroll") for (int n = 0; n < 2; ++n) _Pragma("unroll") for (int k = 0; k < 2; ++k) \
;         acc[ai][bj][m][n] = __builtin_amdgcn_mfma_f32_16x16x32_bf16(Bt[n][k], At[m][k], acc[ai][bj][m][n], 0, 0, 0); __builtin_amdgcn_s_setprio(0); } while (0)
; #define PG8_WAIT_V(n) asm volatile("s_waitcnt vmcnt(" #n ")" ::: "memory")
; #define PG8_WAIT_L(n) asm volatile("s_waitcnt lgkmcnt(" #n ")" ::: "memory")
; #define PG8_BAR __builtin_amdgcn_s_barrier()
; #define PG8_SCHED __builtin_amdgcn_sched_barrier(0)
; template <class Epi, class Sched, bool ALIGN_EPI = false, bool SP2 = false>
; __device__ __forceinline__ void gemm_phase(PG8_LAS unsigned char* lds, const Gemm g, const Sched& S, const Epi& E, const int tid) {
;     ...
;             PG8_WAIT_V(8); PG8_WAIT_L(0); PG8_BAR; PG8_MMA(0, 0, At, B0); PG8_MMA(0, 1, At, B1); PG8_BAR; PG8_SCHED;
;             PG8_LDA(At, 1, 1); PG8_STAGE(PG8_SB(1, 0), b3, voffB); PG8_STAGE(PG8_SB(1, 1), b3 + hstep, voffB); PG8_STAGE(PG8_SA(1, 0), a3, voffA);
;             PG8_WAIT_V(8); PG8_WAIT_L(0); PG8_BAR; PG8_MMA(1, 0, At, B0); PG8_MMA(1, 1, At, B1); PG8_BAR; PG8_SCHED;
	v_mfma_f32_16x16x32_bf16 v[86:89], v[190:193], v[234:237], v[86:89]
	v_mfma_f32_16x16x32_bf16 v[82:85], v[210:213], v[234:237], v[82:85]
	v_mfma_f32_16x16x32_bf16 v[70:73], v[190:193], v[242:245], v[70:73]
	v_mfma_f32_16x16x32_bf16 v[66:69], v[210:213], v[242:245], v[66:69]
	s_setprio 0
	s_add_i32 s38, s51, s83
	v_lshl_add_u64 v[194:195], v[194:195], 0, s[56:57]
	s_mov_b32 m0, s38
	ds_read_b128 v[214:217], v167 offset:49152
	ds_read_b128 v[218:221], v167 offset:50176
	ds_read_b128 v[222:225], v167 offset:51200
	ds_read_b128 v[226:229], v167 offset:52224
	ds_read_b128 v[230:233], v167 offset:53248
	ds_read_b128 v[234:237], v167 offset:54272
	ds_read_b128 v[238:241], v167 offset:55296
	ds_read_b128 v[242:245], v167 offset:56320
	global_load_lds_dwordx4 v[194:195], off
	s_add_i32 m0, s38, 0x2000
	s_add_u32 s38, s74, 0x40080
	v_lshl_add_u64 v[194:195], v[246:247], 0, s[56:57]
	s_addc_u32 s39, s75, 0
	s_add_i32 s51, s59, s83
	global_load_lds_dwordx4 v[194:195], off
	v_lshl_add_u64 v[194:195], s[38:39], 0, v[134:135]
	s_mov_b32 m0, s51
	s_nop 0
	global_load_lds_dwordx4 v[194:195], off
	v_lshl_add_u64 v[194:195], s[38:39], 0, v[130:131]
	s_add_i32 m0, s51, 0x2000
	s_nop 0
	global_load_lds_dwordx4 v[194:195], off
	v_lshl_add_u64 v[194:195], v[248:249], 0, s[56:57]
	s_mov_b32 m0, s88
	s_nop 0
	global_load_lds_dwordx4 v[194:195], off
	v_lshl_add_u64 v[194:195], v[250:251], 0, s[56:57]
	s_mov_b32 m0, s89
	s_nop 0
	global_load_lds_dwordx4 v[194:195], off
	s_waitcnt vmcnt(8)
	s_waitcnt lgkmcnt(0)
	s_setprio 1
	s_barrier
	v_mfma_f32_16x16x32_bf16 v[62:65], v[170:173], v[214:217], v[62:65]
	v_mfma_f32_16x16x32_bf16 v[58:61], v[178:181], v[214:217], v[58:61]
	v_mfma_f32_16x16x32_bf16 v[46:49], v[170:173], v[222:225], v[46:49]
	v_mfma_f32_16x16x32_bf16 v[42:45], v[178:181], v[222:225], v[42:45]
	v_mfma_f32_16x16x32_bf16 v[30:33], v[170:173], v[230:233], v[30:33]
	v_mfma_f32_16x16x32_bf16 v[26:29], v[178:181], v[230:233], v[26:29]
	v_mfma_f32_16x16x32_bf16 v[14:17], v[170:173], v[238:241], v[14:17]
	v_mfma_f32_16x16x32_bf16 v[10:13], v[178:181], v[238:241], v[10:13]
	v_mfma_f32_16x16x32_bf16 v[62:65], v[174:177], v[218:221], v[62:65]
	v_mfma_f32_16x16x32_bf16 v[58:61], v[182:185], v[218:221], v[58:61]
	v_mfma_f32_16x16x32_bf16 v[46:49], v[174:177], v[226:229], v[46:49]
	v_mfma_f32_16x16x32_bf16 v[42:45], v[182:185], v[226:229], v[42:45]
	v_mfma_f32_16x16x32_bf16 v[30:33], v[174:177], v[234:237], v[30:33]
	v_mfma_f32_16x16x32_bf16 v[26:29], v[182:185], v[234:237], v[26:29]
	v_mfma_f32_16x16x32_bf16 v[14:17], v[174:177], v[242:245], v[14:17]
	v_mfma_f32_16x16x32_bf16 v[10:13], v[182:185], v[242:245], v[10:13]
	v_mfma_f32_16x16x32_bf16 v[54:57], v[186:189], v[214:217], v[54:57]
	v_mfma_f32_16x16x32_bf16 v[50:53], v[206:209], v[214:217], v[50:53]
	v_mfma_f32_16x16x32_bf16 v[38:41], v[186:189], v[222:225], v[38:41]
	v_mfma_f32_16x16x32_bf16 v[34:37], v[206:209], v[222:225], v[34:37]
	v_mfma_f32_16x16x32_bf16 v[22:25], v[186:189], v[230:233], v[22:25]
	v_mfma_f32_16x16x32_bf16 v[18:21], v[206:209], v[230:233], v[18:21]
	v_mfma_f32_16x16x32_bf16 v[6:9], v[186:189], v[238:241], v[6:9]
	v_mfma_f32_16x16x32_bf16 v[2:5], v[206:209], v[238:241], v[2:5]
	v_mfma_f32_16x16x32_bf16 v[54:57], v[190:193], v[218:221], v[54:57]
	v_mfma_f32_16x16x32_bf16 v[50:53], v[210:213], v[218:221], v[50:53]
	v_mfma_f32_16x16x32_bf16 v[38:41], v[190:193], v[226:229], v[38:41]
	v_mfma_f32_16x16x32_bf16 v[34:37], v[210:213], v[226:229], v[34:37]
	s_barrier
	v_mfma_f32_16x16x32_bf16 v[22:25], v[190:193], v[234:237], v[22:25]
	v_mfma_f32_16x16x32_bf16 v[18:21], v[210:213], v[234:237], v[18:21]
	v_mfma_f32_16x16x32_bf16 v[6:9], v[190:193], v[242:245], v[6:9]
	v_mfma_f32_16x16x32_bf16 v[2:5], v[210:213], v[242:245], v[2:5]
	s_setprio 0
	s_add_i32 s50, s50, 2
	s_add_u32 s12, s12, 0x100
	s_addc_u32 s13, s13, 0
	s_cmp_gt_u32 s50, 13
	s_cbranch_scc1 .LBB0_211

; #define PG8_STAGE(bufoff, gbase, voff) do { _Pragma("unroll") for (int _i = 0; _i < 2; ++_i) \
;         __builtin_amdgcn_global_load_lds((const unsigned*)((const char*)(gbase) + (voff)[_i]), (PG8_LAS unsigned*)(lds + (bufoff) + ldsw + _i * 8192), 16, 0, 0); } while (0)
; #define PG8_LDA(dst, b, h) do { _Pragma("unroll") for (int m = 0; m < 4; ++m) _Pragma("unroll") for (int k = 0; k < 2; ++k) dst[m][k] = *(const PG8_LAS bf16x8*)(lds + PG8_SA(b, h) + aoff + m * 2048 + k * 1024); } while (0)
; #define PG8_LDB(dst, b, h) do { _Pragma("unroll") for (int n = 0; n < 2; ++n) _Pragma("unroll") for (int k = 0; k < 2; ++k) dst[n][k] = *(const PG8_LAS bf16x8*)(lds + PG8_SB(b, h) + boff + n * 2048 + k * 1024); } while (0)
; #define PG8_MMA(ai, bj, At, Bt) do { __builtin_amdgcn_s_setprio(1); _Pragma("unroll") for (int m = 0; m < 4; ++m) _Pragma("unroll") for (int n = 0; n < 2; ++n) _Pragma("unroll") for (int k = 0; k < 2; ++k) \
;         acc[ai][bj][m][n] = __builtin_amdgcn_mfma_f32_16x16x32_bf16(Bt[n][k], At[m][k], acc[ai][bj][m][n], 0, 0, 0); __builtin_amdgcn_s_setprio(0); } while (0)
; #define PG8_WAIT_V(n) asm volatile("s_waitcnt vmcnt(" #n ")" ::: "memory")
; #define PG8_WAIT_L(n) asm volatile("s_waitcnt lgkmcnt(" #n ")" ::: "memory")
; #define PG8_BAR __builtin_amdgcn_s_barrier()
; #define PG8_SCHED __builtin_amdgcn_sched_barrier(0)
; template <class Epi, class Sched, bool ALIGN_EPI = false, bool SP2 = false>
; __device__ __forceinline__ void gemm_phase(PG8_LAS unsigned char* lds, const Gemm g, const Sched& S, const Epi& E, const int tid) {
;     ...
;             const char* a2 = last ? nA : cA + (size_t)(t + 2) * kstep; const char* b2 = last ? nB : cB + (size_t)(t + 2) * kstep;
;             const char* a3 = a2 + kstep; const char* b3 = b2 + kstep;
;             if (last && has_next) S.a_ready(nxt);
;             if constexpr (SP2) {
;             PG8_LDB(B0, 0, 0); PG8_LDB(B1, 0, 1); PG8_SCHED; PG8_LDA(At, 0, 0); PG8_STAGE(PG8_SA(1, 1), a1 + hstep, voffA);
;             PG8_WAIT_V(8); PG8_WAIT_L(0); PG8_BAR; PG8_MMA(0, 0, At, B0); PG8_MMA(0, 1, At, B1); PG8_BAR; PG8_SCHED;
;             PG8_LDA(At, 0, 1); PG8_STAGE(PG8_SB(0, 0), b2, voffB); PG8_STAGE(PG8_SB(0, 1), b2 + hstep, voffB); PG8_STAGE(PG8_SA(0, 0), a2, voffA);
;             PG8_WAIT_V(8); PG8_WAIT_L(0); PG8_BAR; PG8_MMA(1, 0, At, B0); PG8_MMA(1, 1, At, B1); PG8_BAR; PG8_SCHED;
.LBB0_618:
	s_add_i32 s85, s70, 2
	s_add_u32 s38, s68, 0x80
	s_addc_u32 s39, s69, 0
	s_add_i32 s59, 0, 0x10000
	s_cmp_eq_u32 s81, s70
	s_cselect_b32 s71, s11, s39
	s_cselect_b32 s70, s10, s38
	s_cselect_b32 s39, s67, s51
	s_cselect_b32 s38, s66, s50
	s_add_i32 s86, 0, 0x14000
	v_add_u32_e32 v142, s59, v205
	v_add_u32_e32 v180, s86, v205
	ds_read_b128 v[130:133], v142
	ds_read_b128 v[134:137], v142 offset:1024
	ds_read_b128 v[138:141], v142 offset:2048
	ds_read_b128 v[142:145], v142 offset:3072
	ds_read_b128 v[146:149], v180
	ds_read_b128 v[150:153], v180 offset:1024
	ds_read_b128 v[176:179], v180 offset:2048
	ds_read_b128 v[180:183], v180 offset:3072
	v_lshl_add_u64 v[192:193], s[68:69], 0, v[172:173]
	s_add_i32 m0, s73, 0xc000
	ds_read_b128 v[184:187], v207
	ds_read_b128 v[188:191], v207 offset:1024
	ds_read_b128 v[208:211], v207 offset:2048
	ds_read_b128 v[212:215], v207 offset:3072
	ds_read_b128 v[216:219], v207 offset:4096
	ds_read_b128 v[220:223], v207 offset:5120
	ds_read_b128 v[224:227], v207 offset:6144
	ds_read_b128 v[228:231], v207 offset:7168
	global_load_lds_dwordx4 v[192:193], off
	v_lshl_add_u64 v[192:193], s[68:69], 0, v[174:175]
	s_add_i32 m0, s73, 0xe000
	s_nop 0
	global_load_lds_dwordx4 v[192:193], off
	s_waitcnt vmcnt(8)
	s_waitcnt lgkmcnt(0)
	s_setprio 1
	s_barrier
	v_mfma_f32_16x16x32_bf16 v[126:129], v[130:133], v[184:187], v[126:129]
	v_mfma_f32_16x16x32_bf16 v[122:125], v[138:141], v[184:187], v[122:125]
	v_mfma_f32_16x16x32_bf16 v[110:113], v[130:133], v[208:211], v[110:113]
	v_mfma_f32_16x16x32_bf16 v[106:109], v[138:141], v[208:211], v[106:109]
	v_mfma_f32_16x16x32_bf16 v[94:97], v[130:133], v[216:219], v[94:97]
	v_mfma_f32_16x16x32_bf16 v[90:93], v[138:141], v[216:219], v[90:93]
	v_mfma_f32_16x16x32_bf16 v[78:81], v[130:133], v[224:227], v[78:81]
	v_mfma_f32_16x16x32_bf16 v[74:77], v[138:141], v[224:227], v[74:77]
	v_mfma_f32_16x16x32_bf16 v[126:129], v[134:137], v[188:191], v[126:129]
	v_mfma_f32_16x16x32_bf16 v[122:125], v[142:145], v[188:191], v[122:125]
	v_mfma_f32_16x16x32_bf16 v[110:113], v[134:137], v[212:215], v[110:113]
	v_mfma_f32_16x16x32_bf16 v[106:109], v[142:145], v[212:215], v[106:109]
	v_mfma_f32_16x16x32_bf16 v[94:97], v[134:137], v[220:223], v[94:97]
	v_mfma_f32_16x16x32_bf16 v[90:93], v[142:145], v[220:223], v[90:93]
	v_mfma_f32_16x16x32_bf16 v[78:81], v[134:137], v[228:231], v[78:81]
	v_mfma_f32_16x16x32_bf16 v[74:77], v[142:145], v[228:231], v[74:77]
	v_mfma_f32_16x16x32_bf16 v[118:121], v[146:149], v[184:187], v[118:121]
	v_mfma_f32_16x16x32_bf16 v[114:117], v[176:179], v[184:187], v[114:117]
	v_mfma_f32_16x16x32_bf16 v[102:105], v[146:149], v[208:211], v[102:105]
	v_mfma_f32_16x16x32_bf16 v[98:101], v[176:179], v[208:211], v[98:101]
	v_mfma_f32_16x16x32_bf16 v[86:89], v[146:149], v[216:219], v[86:89]
	v_mfma_f32_16x16x32_bf16 v[82:85], v[176:179], v[216:219], v[82:85]
	v_mfma_f32_16x16x32_bf16 v[70:73], v[146:149], v[224:227], v[70:73]
	v_mfma_f32_16x16x32_bf16 v[66:69], v[176:179], v[224:227], v[66:69]
	v_mfma_f32_16x16x32_bf16 v[118:121], v[150:153], v[188:191], v[118:121]
	v_mfma_f32_16x16x32_bf16 v[114:117], v[180:183], v[188:191], v[114:117]
	v_mfma_f32_16x16x32_bf16 v[102:105], v[150:153], v[212:215], v[102:105]
	v_mfma_f32_16x16x32_bf16 v[98:101], v[180:183], v[212:215], v[98:101]
	s_barrier
	v_mfma_f32_16x16x32_bf16 v[86:89], v[150:153], v[220:223], v[86:89]
	v_mfma_f32_16x16x32_bf16 v[82:85], v[180:183], v[220:223], v[82:85]
	v_mfma_f32_16x16x32_bf16 v[70:73], v[150:153], v[228:231], v[70:73]
	v_mfma_f32_16x16x32_bf16 v[66:69], v[180:183], v[228:231], v[66:69]
	s_setprio 0
	s_add_i32 s59, s59, s72
	v_lshl_add_u64 v[192:193], s[38:39], 0, v[0:1]
	s_mov_b32 m0, s59
	ds_read_b128 v[184:187], v207 offset:16384
	ds_read_b128 v[188:191], v207 offset:17408
	ds_read_b128 v[208:211], v207 offset:18432
	ds_read_b128 v[212:215], v207 offset:19456
	ds_read_b128 v[216:219], v207 offset:20480
	ds_read_b128 v[220:223], v207 offset:21504
	ds_read_b128 v[224:227], v207 offset:22528
	ds_read_b128 v[228:231], v207 offset:23552
	global_load_lds_dwordx4 v[192:193], off
	s_add_i32 m0, s59, 0x2000
	v_lshl_add_u64 v[194:195], s[38:39], 0, v[166:167]
	s_add_u32 s38, s38, s14
	s_addc_u32 s39, s39, 0
	s_add_i32 s59, s86, s72
	global_load_lds_dwordx4 v[194:195], off
	v_lshl_add_u64 v[232:233], s[38:39], 0, v[0:1]
	s_mov_b32 m0, s59
	v_lshl_add_u64 v[234:235], s[38:39], 0, v[166:167]
	global_load_lds_dwordx4 v[232:233], off
	s_add_i32 m0, s59, 0x2000
	v_lshl_add_u64 v[236:237], s[70:71], 0, v[170:171]
	global_load_lds_dwordx4 v[234:235], off
	s_mov_b32 m0, s73
	v_lshl_add_u64 v[238:239], s[70:71], 0, v[168:169]
	global_load_lds_dwordx4 v[236:237], off
	s_mov_b32 m0, s74
	s_nop 0
	global_load_lds_dwordx4 v[238:239], off
	s_waitcnt vmcnt(8)
	s_waitcnt lgkmcnt(0)
	s_setprio 1
	s_barrier
; #define PG8_STAGE(bufoff, gbase, voff) do { _Pragma("unroll") for (int _i = 0; _i < 2; ++_i) \
;         __builtin_amdgcn_global_load_lds((const unsigned*)((const char*)(gbase) + (voff)[_i]), (PG8_LAS unsigned*)(lds + (bufoff) + ldsw + _i * 8192), 16, 0, 0); } while (0)
; #define PG8_LDA(dst, b, h) do { _Pragma("unroll") for (int m = 0; m < 4; ++m) _Pragma("unroll") for (int k = 0; k < 2; ++k) dst[m][k] = *(const PG8_LAS bf16x8*)(lds + PG8_SA(b, h) + aoff + m * 2048 + k * 1024); } while (0)
; #define PG8_LDB(dst, b, h) do { _Pragma("unroll") for (int n = 0; n < 2; ++n) _Pragma("unroll") for (int k = 0; k < 2; ++k) dst[n][k] = *(const PG8_LAS bf16x8*)(lds + PG8_SB(b, h) + boff + n * 2048 + k * 1024); } while (0)
; #define PG8_MMA(ai, bj, At, Bt) do { __builtin_amdgcn_s_setprio(1); _Pragma("unroll") for (int m = 0; m < 4; ++m) _Pragma("unroll") for (int n = 0; n < 2; ++n) _Pragma("unroll") for (int k = 0; k < 2; ++k) \
;         acc[ai][bj][m][n] = __builtin_amdgcn_mfma_f32_16x16x32_bf16(Bt[n][k], At[m][k], acc[ai][bj][m][n], 0, 0, 0); __builtin_amdgcn_s_setprio(0); } while (0)
; #define PG8_WAIT_V(n) asm volatile("s_waitcnt vmcnt(" #n ")" ::: "memory")
; #define PG8_WAIT_L(n) asm volatile("s_waitcnt lgkmcnt(" #n ")" ::: "memory")
; #define PG8_BAR __builtin_amdgcn_s_barrier()
; #define PG8_SCHED __builtin_amdgcn_sched_barrier(0)
; template <class Epi, class Sched, bool ALIGN_EPI = false, bool SP2 = false>
; __device__ __forceinline__ void gemm_phase(PG8_LAS unsigned char* lds, const Gemm g, const Sched& S, const Epi& E, const int tid) {
;     ...
;             PG8_WAIT_V(8); PG8_WAIT_L(0); PG8_BAR; PG8_MMA(1, 0, At, B0); PG8_MMA(1, 1, At, B1); PG8_BAR; PG8_SCHED;
;             PG8_LDB(B0, 1, 0); PG8_LDB(B1, 1, 1); PG8_SCHED; PG8_LDA(At, 1, 0); PG8_STAGE(PG8_SA(0, 1), a2 + hstep, voffA);
;             PG8_WAIT_V(8); PG8_WAIT_L(0); PG8_BAR; PG8_MMA(0, 0, At, B0); PG8_MMA(0, 1, At, B1); PG8_BAR; PG8_SCHED;
	v_mfma_f32_16x16x32_bf16 v[62:65], v[130:133], v[184:187], v[62:65]
	v_mfma_f32_16x16x32_bf16 v[58:61], v[138:141], v[184:187], v[58:61]
	v_mfma_f32_16x16x32_bf16 v[46:49], v[130:133], v[208:211], v[46:49]
	v_mfma_f32_16x16x32_bf16 v[42:45], v[138:141], v[208:211], v[42:45]
	v_mfma_f32_16x16x32_bf16 v[30:33], v[130:133], v[216:219], v[30:33]
	v_mfma_f32_16x16x32_bf16 v[26:29], v[138:141], v[216:219], v[26:29]
	v_mfma_f32_16x16x32_bf16 v[14:17], v[130:133], v[224:227], v[14:17]
	v_mfma_f32_16x16x32_bf16 v[10:13], v[138:141], v[224:227], v[10:13]
	v_mfma_f32_16x16x32_bf16 v[62:65], v[134:137], v[188:191], v[62:65]
	v_mfma_f32_16x16x32_bf16 v[58:61], v[142:145], v[188:191], v[58:61]
	v_mfma_f32_16x16x32_bf16 v[46:49], v[134:137], v[212:215], v[46:49]
	v_mfma_f32_16x16x32_bf16 v[42:45], v[142:145], v[212:215], v[42:45]
	v_mfma_f32_16x16x32_bf16 v[30:33], v[134:137], v[220:223], v[30:33]
	v_mfma_f32_16x16x32_bf16 v[26:29], v[142:145], v[220:223], v[26:29]
	v_mfma_f32_16x16x32_bf16 v[14:17], v[134:137], v[228:231], v[14:17]
	v_mfma_f32_16x16x32_bf16 v[10:13], v[142:145], v[228:231], v[10:13]
	v_mfma_f32_16x16x32_bf16 v[54:57], v[146:149], v[184:187], v[54:57]
	v_mfma_f32_16x16x32_bf16 v[50:53], v[176:179], v[184:187], v[50:53]
	v_mfma_f32_16x16x32_bf16 v[38:41], v[146:149], v[208:211], v[38:41]
	v_mfma_f32_16x16x32_bf16 v[34:37], v[176:179], v[208:211], v[34:37]
	v_mfma_f32_16x16x32_bf16 v[22:25], v[146:149], v[216:219], v[22:25]
	v_mfma_f32_16x16x32_bf16 v[18:21], v[176:179], v[216:219], v[18:21]
	v_mfma_f32_16x16x32_bf16 v[6:9], v[146:149], v[224:227], v[6:9]
	v_mfma_f32_16x16x32_bf16 v[2:5], v[176:179], v[224:227], v[2:5]
	v_mfma_f32_16x16x32_bf16 v[54:57], v[150:153], v[188:191], v[54:57]
	v_mfma_f32_16x16x32_bf16 v[50:53], v[180:183], v[188:191], v[50:53]
	v_mfma_f32_16x16x32_bf16 v[38:41], v[150:153], v[212:215], v[38:41]
	v_mfma_f32_16x16x32_bf16 v[34:37], v[180:183], v[212:215], v[34:37]
	s_barrier
	v_mfma_f32_16x16x32_bf16 v[22:25], v[150:153], v[220:223], v[22:25]
	v_mfma_f32_16x16x32_bf16 v[18:21], v[180:183], v[220:223], v[18:21]
	v_mfma_f32_16x16x32_bf16 v[6:9], v[150:153], v[228:231], v[6:9]
	v_mfma_f32_16x16x32_bf16 v[2:5], v[180:183], v[228:231], v[2:5]
	s_setprio 0
	s_add_i32 s59, 0, 0x18000
	s_add_i32 s86, 0, 0x1c000
	v_add_u32_e32 v142, s59, v205
	v_add_u32_e32 v180, s86, v205
	ds_read_b128 v[130:133], v142
	ds_read_b128 v[134:137], v142 offset:1024
	ds_read_b128 v[138:141], v142 offset:2048
	ds_read_b128 v[142:145], v142 offset:3072
	ds_read_b128 v[146:149], v180
	ds_read_b128 v[150:153], v180 offset:1024
	ds_read_b128 v[176:179], v180 offset:2048
	ds_read_b128 v[180:183], v180 offset:3072
	s_add_u32 s38, s70, s14
	s_addc_u32 s39, s71, 0
	s_mov_b32 m0, s75
	v_lshl_add_u64 v[240:241], s[38:39], 0, v[170:171]
	ds_read_b128 v[184:187], v207 offset:32768
	ds_read_b128 v[188:191], v207 offset:33792
	ds_read_b128 v[208:211], v207 offset:34816
	ds_read_b128 v[212:215], v207 offset:35840
	ds_read_b128 v[216:219], v207 offset:36864
	ds_read_b128 v[220:223], v207 offset:37888
	ds_read_b128 v[224:227], v207 offset:38912
	ds_read_b128 v[228:231], v207 offset:39936
	global_load_lds_dwordx4 v[240:241], off
	v_lshl_add_u64 v[240:241], s[38:39], 0, v[168:169]
	s_mov_b32 m0, s76
	s_nop 0
	global_load_lds_dwordx4 v[240:241], off
	s_waitcnt vmcnt(8)
	s_waitcnt lgkmcnt(0)
	s_setprio 1
	s_barrier
	v_mfma_f32_16x16x32_bf16 v[126:129], v[130:133], v[184:187], v[126:129]
	v_mfma_f32_16x16x32_bf16 v[122:125], v[138:141], v[184:187], v[122:125]
	v_mfma_f32_16x16x32_bf16 v[110:113], v[130:133], v[208:211], v[110:113]
	v_mfma_f32_16x16x32_bf16 v[106:109], v[138:141], v[208:211], v[106:109]
	v_mfma_f32_16x16x32_bf16 v[94:97], v[130:133], v[216:219], v[94:97]
	v_mfma_f32_16x16x32_bf16 v[90:93], v[138:141], v[216:219], v[90:93]
	v_mfma_f32_16x16x32_bf16 v[78:81], v[130:133], v[224:227], v[78:81]
	v_mfma_f32_16x16x32_bf16 v[74:77], v[138:141], v[224:227], v[74:77]
	v_mfma_f32_16x16x32_bf16 v[126:129], v[134:137], v[188:191], v[126:129]
	v_mfma_f32_16x16x32_bf16 v[122:125], v[142:145], v[188:191], v[122:125]
	v_mfma_f32_16x16x32_bf16 v[110:113], v[134:137], v[212:215], v[110:113]
	v_mfma_f32_16x16x32_bf16 v[106:109], v[142:145], v[212:215], v[106:109]
	v_mfma_f32_16x16x32_bf16 v[94:97], v[134:137], v[220:223], v[94:97]
	v_mfma_f32_16x16x32_bf16 v[90:93], v[142:145], v[220:223], v[90:93]
	v_mfma_f32_16x16x32_bf16 v[78:81], v[134:137], v[228:231], v[78:81]
	v_mfma_f32_16x16x32_bf16 v[74:77], v[142:145], v[228:231], v[74:77]
	v_mfma_f32_16x16x32_bf16 v[118:121], v[146:149], v[184:187], v[118:121]
	v_mfma_f32_16x16x32_bf16 v[114:117], v[176:179], v[184:187], v[114:117]
	v_mfma_f32_16x16x32_bf16 v[102:105], v[146:149], v[208:211], v[102:105]
	v_mfma_f32_16x16x32_bf16 v[98:101], v[176:179], v[208:211], v[98:101]
	v_mfma_f32_16x16x32_bf16 v[86:89], v[146:149], v[216:219], v[86:89]
	v_mfma_f32_16x16x32_bf16 v[82:85], v[176:179], v[216:219], v[82:85]
	v_mfma_f32_16x16x32_bf16 v[70:73], v[146:149], v[224:227], v[70:73]
	v_mfma_f32_16x16x32_bf16 v[66:69], v[176:179], v[224:227], v[66:69]
	v_mfma_f32_16x16x32_bf16 v[118:121], v[150:153], v[188:191], v[118:121]
	v_mfma_f32_16x16x32_bf16 v[114:117], v[180:183], v[188:191], v[114:117]
	v_mfma_f32_16x16x32_bf16 v[102:105], v[150:153], v[212:215], v[102:105]
	v_mfma_f32_16x16x32_bf16 v[98:101], v[180:183], v[212:215], v[98:101]
	s_barrier
; #define PG8_STAGE(bufoff, gbase, voff) do { _Pragma("unroll") for (int _i = 0; _i < 2; ++_i) \
;         __builtin_amdgcn_global_load_lds((const unsigned*)((const char*)(gbase) + (voff)[_i]), (PG8_LAS unsigned*)(lds + (bufoff) + ldsw + _i * 8192), 16, 0, 0); } while (0)
; #define PG8_LDA(dst, b, h) do { _Pragma("unroll") for (int m = 0; m < 4; ++m) _Pragma("unroll") for (int k = 0; k < 2; ++k) dst[m][k] = *(const PG8_LAS bf16x8*)(lds + PG8_SA(b, h) + aoff + m * 2048 + k * 1024); } while (0)
; #define PG8_MMA(ai, bj, At, Bt) do { __builtin_amdgcn_s_setprio(1); _Pragma("unroll") for (int m = 0; m < 4; ++m) _Pragma("unroll") for (int n = 0; n < 2; ++n) _Pragma("unroll") for (int k = 0; k < 2; ++k) \
;         acc[ai][bj][m][n] = __builtin_amdgcn_mfma_f32_16x16x32_bf16(Bt[n][k], At[m][k], acc[ai][bj][m][n], 0, 0, 0); __builtin_amdgcn_s_setprio(0); } while (0)
; #define PG8_WAIT_V(n) asm volatile("s_waitcnt vmcnt(" #n ")" ::: "memory")
; #define PG8_WAIT_L(n) asm volatile("s_waitcnt lgkmcnt(" #n ")" ::: "memory")
; #define PG8_BAR __builtin_amdgcn_s_barrier()
; #define PG8_SCHED __builtin_amdgcn_sched_barrier(0)
; template <class Epi, class Sched, bool ALIGN_EPI = false, bool SP2 = false>
; __device__ __forceinline__ void gemm_phase(PG8_LAS unsigned char* lds, const Gemm g, const Sched& S, const Epi& E, const int tid) {
;     ...
;             PG8_WAIT_V(8); PG8_WAIT_L(0); PG8_BAR; PG8_MMA(0, 0, At, B0); PG8_MMA(0, 1, At, B1); PG8_BAR; PG8_SCHED;
;             PG8_LDA(At, 1, 1); PG8_STAGE(PG8_SB(1, 0), b3, voffB); PG8_STAGE(PG8_SB(1, 1), b3 + hstep, voffB); PG8_STAGE(PG8_SA(1, 0), a3, voffA);
;             PG8_WAIT_V(8); PG8_WAIT_L(0); PG8_BAR; PG8_MMA(1, 0, At, B0); PG8_MMA(1, 1, At, B1); PG8_BAR; PG8_SCHED;
;     ...
;         if constexpr (ALIGN_EPI) { if (wr == 0) PG8_BAR; }
	v_mfma_f32_16x16x32_bf16 v[86:89], v[150:153], v[220:223], v[86:89]
	v_mfma_f32_16x16x32_bf16 v[82:85], v[180:183], v[220:223], v[82:85]
	v_mfma_f32_16x16x32_bf16 v[70:73], v[150:153], v[228:231], v[70:73]
	v_mfma_f32_16x16x32_bf16 v[66:69], v[180:183], v[228:231], v[66:69]
	s_setprio 0
	s_add_i32 s38, s59, s72
	v_lshl_add_u64 v[192:193], v[192:193], 0, s[56:57]
	s_mov_b32 m0, s38
	ds_read_b128 v[184:187], v207 offset:49152
	ds_read_b128 v[188:191], v207 offset:50176
	ds_read_b128 v[208:211], v207 offset:51200
	ds_read_b128 v[212:215], v207 offset:52224
	ds_read_b128 v[216:219], v207 offset:53248
	ds_read_b128 v[220:223], v207 offset:54272
	ds_read_b128 v[224:227], v207 offset:55296
	ds_read_b128 v[228:231], v207 offset:56320
	global_load_lds_dwordx4 v[192:193], off
	v_lshl_add_u64 v[192:193], v[194:195], 0, s[56:57]
	s_add_i32 m0, s38, 0x2000
	s_add_i32 s38, s86, s72
	global_load_lds_dwordx4 v[192:193], off
	v_lshl_add_u64 v[192:193], v[232:233], 0, s[56:57]
	s_mov_b32 m0, s38
	s_nop 0
	global_load_lds_dwordx4 v[192:193], off
	v_lshl_add_u64 v[192:193], v[234:235], 0, s[56:57]
	s_add_i32 m0, s38, 0x2000
	s_nop 0
	global_load_lds_dwordx4 v[192:193], off
	v_lshl_add_u64 v[192:193], v[236:237], 0, s[56:57]
	s_mov_b32 m0, s79
	s_nop 0
	global_load_lds_dwordx4 v[192:193], off
	v_lshl_add_u64 v[192:193], v[238:239], 0, s[56:57]
	s_mov_b32 m0, s80
	s_nop 0
	global_load_lds_dwordx4 v[192:193], off
	s_waitcnt vmcnt(8)
	s_waitcnt lgkmcnt(0)
	s_setprio 1
	s_barrier
	v_mfma_f32_16x16x32_bf16 v[62:65], v[130:133], v[184:187], v[62:65]
	v_mfma_f32_16x16x32_bf16 v[58:61], v[138:141], v[184:187], v[58:61]
	v_mfma_f32_16x16x32_bf16 v[46:49], v[130:133], v[208:211], v[46:49]
	v_mfma_f32_16x16x32_bf16 v[42:45], v[138:141], v[208:211], v[42:45]
	v_mfma_f32_16x16x32_bf16 v[30:33], v[130:133], v[216:219], v[30:33]
	v_mfma_f32_16x16x32_bf16 v[26:29], v[138:141], v[216:219], v[26:29]
	v_mfma_f32_16x16x32_bf16 v[14:17], v[130:133], v[224:227], v[14:17]
	v_mfma_f32_16x16x32_bf16 v[10:13], v[138:141], v[224:227], v[10:13]
	v_mfma_f32_16x16x32_bf16 v[62:65], v[134:137], v[188:191], v[62:65]
	v_mfma_f32_16x16x32_bf16 v[58:61], v[142:145], v[188:191], v[58:61]
	v_mfma_f32_16x16x32_bf16 v[46:49], v[134:137], v[212:215], v[46:49]
	v_mfma_f32_16x16x32_bf16 v[42:45], v[142:145], v[212:215], v[42:45]
	v_mfma_f32_16x16x32_bf16 v[30:33], v[134:137], v[220:223], v[30:33]
	v_mfma_f32_16x16x32_bf16 v[26:29], v[142:145], v[220:223], v[26:29]
	v_mfma_f32_16x16x32_bf16 v[14:17], v[134:137], v[228:231], v[14:17]
	v_mfma_f32_16x16x32_bf16 v[10:13], v[142:145], v[228:231], v[10:13]
	v_mfma_f32_16x16x32_bf16 v[54:57], v[146:149], v[184:187], v[54:57]
	v_mfma_f32_16x16x32_bf16 v[50:53], v[176:179], v[184:187], v[50:53]
	v_mfma_f32_16x16x32_bf16 v[38:41], v[146:149], v[208:211], v[38:41]
	v_mfma_f32_16x16x32_bf16 v[34:37], v[176:179], v[208:211], v[34:37]
	v_mfma_f32_16x16x32_bf16 v[22:25], v[146:149], v[216:219], v[22:25]
	v_mfma_f32_16x16x32_bf16 v[18:21], v[176:179], v[216:219], v[18:21]
	v_mfma_f32_16x16x32_bf16 v[6:9], v[146:149], v[224:227], v[6:9]
	v_mfma_f32_16x16x32_bf16 v[2:5], v[176:179], v[224:227], v[2:5]
	v_mfma_f32_16x16x32_bf16 v[54:57], v[150:153], v[188:191], v[54:57]
	v_mfma_f32_16x16x32_bf16 v[50:53], v[180:183], v[188:191], v[50:53]
	v_mfma_f32_16x16x32_bf16 v[38:41], v[150:153], v[212:215], v[38:41]
	v_mfma_f32_16x16x32_bf16 v[34:37], v[180:183], v[212:215], v[34:37]
	s_barrier
	v_mfma_f32_16x16x32_bf16 v[22:25], v[150:153], v[220:223], v[22:25]
	v_mfma_f32_16x16x32_bf16 v[18:21], v[180:183], v[220:223], v[18:21]
	v_mfma_f32_16x16x32_bf16 v[6:9], v[150:153], v[228:231], v[6:9]
	v_mfma_f32_16x16x32_bf16 v[2:5], v[180:183], v[228:231], v[2:5]
	s_setprio 0
	s_add_u32 s68, s68, 0x100
	s_addc_u32 s69, s69, 0
	s_add_u32 s50, s50, 0x100
	s_addc_u32 s51, s51, 0
	s_cmp_ge_u32 s85, s78
	s_mov_b32 s70, s85
	s_cbranch_scc0 .LBB0_618
	s_and_b64 vcc, exec, s[22:23]
	s_cbranch_vccz .LBB0_621
	s_barrier
